# speedup vs baseline: 1.0142x; 1.0142x over previous
; DI void ln_row(float* yrow, bf16_t* xb, const float* g, const float* b, int lane, float* yout = nullptr) {
;     f32x4* xr = (f32x4*)yrow + lane; f32x4* xo = yout ? (f32x4*)yout + lane : xr;
;     f32x4 v[4]; float s = 0.f;
; #pragma unroll
;     for (int j = 0; j < 4; ++j) { v[j] = xr[64 * j]; s += (v[j].x + v[j].y) + (v[j].z + v[j].w); }
; DI void ln_phase(unsigned char* lds, int l, int which) {
;     ...
;         int m = gw;
;         for (; m + NGW < MP; m += 2 * NGW) ln_row2(Y + (size_t)m * DM, Y + (size_t)(m + NGW) * DM, XB + (size_t)m * DM, XB + (size_t)(m + NGW) * DM, g, b, lane);
;         if (m < MP) ln_row(Y + (size_t)m * DM, XB + (size_t)m * DM, g, b, lane);
.Lmy_pfp0_j:
	s_add_u32 s48, s48, s100
	s_addc_u32 s49, s49, 0
	s_add_i32 s56, s57, 0
	v_lshrrev_b32_e32 v108, 3, v1
	v_mul_u32_u24_e32 v108, 5632, v108
	v_and_b32_e32 v109, 7, v1
	v_lshl_add_u32 v108, v109, 4, v108
	s_lshl_b32 s34, s5, 12
	s_lshl_b32 s35, s5, 11
	s_lshl_b32 s6, s4, 12
	s_add_u32 s8, s44, s6
	s_addc_u32 s9, s45, 0
	s_lshl_b32 s6, s4, 11
	s_add_u32 s10, s42, s6
	s_addc_u32 s11, s43, 0
	s_mov_b32 s6, s8
	s_mov_b32 s7, s9
	s_mov_b32 s54, s4
	global_load_dwordx4 v[36:39], v2, s[6:7]
	global_load_dwordx4 v[40:43], v2, s[6:7] offset:1024
	global_load_dwordx4 v[44:47], v2, s[6:7] offset:2048
	global_load_dwordx4 v[48:51], v2, s[6:7] offset:3072
	s_add_u32 s6, s6, s34
	s_addc_u32 s7, s7, 0
	s_add_i32 s54, s54, s5
	global_load_dwordx4 v[52:55], v2, s[6:7]
	global_load_dwordx4 v[56:59], v2, s[6:7] offset:1024
	global_load_dwordx4 v[60:63], v2, s[6:7] offset:2048
	global_load_dwordx4 v[64:67], v2, s[6:7] offset:3072
	s_add_u32 s6, s6, s34
	s_addc_u32 s7, s7, 0
	s_add_i32 s54, s54, s5
	s_waitcnt vmcnt(4)
.Lmy_lnp0_b0:
	s_cmp_ge_i32 s54, 0x8000
	s_cbranch_scc1 .Lmy_lnp0_n0
	global_load_dwordx4 v[68:71], v2, s[6:7]
	global_load_dwordx4 v[72:75], v2, s[6:7] offset:1024
	global_load_dwordx4 v[76:79], v2, s[6:7] offset:2048
	global_load_dwordx4 v[80:83], v2, s[6:7] offset:3072
	s_add_u32 s6, s6, s34
	s_addc_u32 s7, s7, 0
	s_add_i32 s54, s54, s5

; DI void ln_row(float* yrow, bf16_t* xb, const float* g, const float* b, int lane, float* yout = nullptr) {
;     ...
;     f32x4 v[4]; float s = 0.f;
; #pragma unroll
;     for (int j = 0; j < 4; ++j) { v[j] = xr[64 * j]; s += (v[j].x + v[j].y) + (v[j].z + v[j].w); }
; DI void ln_phase(unsigned char* lds, int l, int which) {
;     ...
;         int m = gw;
;         for (; m + NGW < MP; m += 2 * NGW) ln_row2(Y + (size_t)m * DM, Y + (size_t)(m + NGW) * DM, XB + (size_t)m * DM, XB + (size_t)(m + NGW) * DM, g, b, lane);
;         if (m < MP) ln_row(Y + (size_t)m * DM, XB + (size_t)m * DM, g, b, lane);
.Lmy_lnp0_b1:
	s_cmp_ge_i32 s54, 0x8000
	s_cbranch_scc1 .Lmy_lnp0_n1
	global_load_dwordx4 v[36:39], v2, s[6:7]
	global_load_dwordx4 v[40:43], v2, s[6:7] offset:1024
	global_load_dwordx4 v[44:47], v2, s[6:7] offset:2048
	global_load_dwordx4 v[48:51], v2, s[6:7] offset:3072
	s_add_u32 s6, s6, s34
	s_addc_u32 s7, s7, 0
	s_add_i32 s54, s54, s5

; DI void ln_row(float* yrow, bf16_t* xb, const float* g, const float* b, int lane, float* yout = nullptr) {
;     ...
;     f32x4 v[4]; float s = 0.f;
; #pragma unroll
;     for (int j = 0; j < 4; ++j) { v[j] = xr[64 * j]; s += (v[j].x + v[j].y) + (v[j].z + v[j].w); }
; DI void ln_phase(unsigned char* lds, int l, int which) {
;     ...
;         int m = gw;
;         for (; m + NGW < MP; m += 2 * NGW) ln_row2(Y + (size_t)m * DM, Y + (size_t)(m + NGW) * DM, XB + (size_t)m * DM, XB + (size_t)(m + NGW) * DM, g, b, lane);
;         if (m < MP) ln_row(Y + (size_t)m * DM, XB + (size_t)m * DM, g, b, lane);
.Lmy_lnp0_b2:
	s_cmp_ge_i32 s54, 0x8000
	s_cbranch_scc1 .Lmy_lnp0_n2
	global_load_dwordx4 v[52:55], v2, s[6:7]
	global_load_dwordx4 v[56:59], v2, s[6:7] offset:1024
	global_load_dwordx4 v[60:63], v2, s[6:7] offset:2048
	global_load_dwordx4 v[64:67], v2, s[6:7] offset:3072
	s_add_u32 s6, s6, s34
	s_addc_u32 s7, s7, 0
	s_add_i32 s54, s54, s5

; DI void ln_row(float* yrow, bf16_t* xb, const float* g, const float* b, int lane, float* yout = nullptr) {
;     f32x4* xr = (f32x4*)yrow + lane; f32x4* xo = yout ? (f32x4*)yout + lane : xr;
;     f32x4 v[4]; float s = 0.f;
; #pragma unroll
;     for (int j = 0; j < 4; ++j) { v[j] = xr[64 * j]; s += (v[j].x + v[j].y) + (v[j].z + v[j].w); }
; DI void ln_phase(unsigned char* lds, int l, int which) {
;     ...
;         for (int m = MP + bid * 64 + wid; m < MP + bid * 64 + 64; m += 16) ln_row2(Y + (size_t)m * DM, Y + (size_t)(m + 8) * DM, XB + (size_t)m * DM, XB + (size_t)(m + 8) * DM, g, b, lane);
.LBB0_381:
	s_or_b64 exec, exec, s[40:41]
	s_lshl_b32 s4, s72, 6
	v_add_u32_e32 v2, s4, v162
	v_add_u32_e32 v34, 0x8000, v2
	s_add_i32 s4, s4, 0x8040
	v_cmp_gt_i32_e32 vcc, s4, v34
	s_barrier
	s_and_saveexec_b64 s[42:43], vcc
	s_mov_b32 s5, 0xf800000
	s_mov_b32 s8, 0x3a00000
	s_mov_b64 s[48:49], 0x8000
	s_mov_b64 s[50:51], 0x10000
	s_cbranch_execz .LBB0_384
	s_mov_b64 s[42:43], exec
	s_add_u32 s50, s46, 0x3a00000
	s_addc_u32 s51, s47, 0
	v_readfirstlane_b32 s4, v162
	s_lshl_b32 s6, s72, 6
	s_add_i32 s4, s4, s6
	s_add_i32 s4, s4, 0x8000
	s_add_i32 s52, s6, 0x8040
	s_mov_b32 s5, 8
	v_lshlrev_b32_e32 v2, 4, v1
	v_lshlrev_b32_e32 v3, 3, v1
	global_load_dwordx4 v[4:7], v2, s[58:59]
	global_load_dwordx4 v[8:11], v2, s[58:59] offset:1024
	global_load_dwordx4 v[12:15], v2, s[58:59] offset:2048
	global_load_dwordx4 v[16:19], v2, s[58:59] offset:3072
	global_load_dwordx4 v[20:23], v2, s[60:61]
	global_load_dwordx4 v[24:27], v2, s[60:61] offset:1024
	global_load_dwordx4 v[28:31], v2, s[60:61] offset:2048
	global_load_dwordx4 v[32:35], v2, s[60:61] offset:3072
	s_lshl_b32 s34, s5, 12
	s_lshl_b32 s35, s5, 11
	s_lshl_b32 s6, s4, 12
	s_add_u32 s8, s44, s6
	s_addc_u32 s9, s45, 0
	s_lshl_b32 s6, s4, 11
	s_add_u32 s10, s50, s6
	s_addc_u32 s11, s51, 0
	s_mov_b32 s6, s8
	s_mov_b32 s7, s9
	s_mov_b32 s54, s4
	global_load_dwordx4 v[36:39], v2, s[6:7]
	global_load_dwordx4 v[40:43], v2, s[6:7] offset:1024
	global_load_dwordx4 v[44:47], v2, s[6:7] offset:2048
	global_load_dwordx4 v[48:51], v2, s[6:7] offset:3072
	s_add_u32 s6, s6, s34
	s_addc_u32 s7, s7, 0
	s_add_i32 s54, s54, s5
	global_load_dwordx4 v[52:55], v2, s[6:7]
	global_load_dwordx4 v[56:59], v2, s[6:7] offset:1024
	global_load_dwordx4 v[60:63], v2, s[6:7] offset:2048
	global_load_dwordx4 v[64:67], v2, s[6:7] offset:3072
	s_add_u32 s6, s6, s34
	s_addc_u32 s7, s7, 0
	s_add_i32 s54, s54, s5
	s_waitcnt vmcnt(4)
.Lmy_lns0_b0:
	s_cmp_ge_i32 s54, s52
	s_cbranch_scc1 .Lmy_lns0_n0
	global_load_dwordx4 v[68:71], v2, s[6:7]
	global_load_dwordx4 v[72:75], v2, s[6:7] offset:1024
	global_load_dwordx4 v[76:79], v2, s[6:7] offset:2048
	global_load_dwordx4 v[80:83], v2, s[6:7] offset:3072
	s_add_u32 s6, s6, s34
	s_addc_u32 s7, s7, 0
	s_add_i32 s54, s54, s5

; DI void ln_row(float* yrow, bf16_t* xb, const float* g, const float* b, int lane, float* yout = nullptr) {
;     ...
;     f32x4 v[4]; float s = 0.f;
; #pragma unroll
;     for (int j = 0; j < 4; ++j) { v[j] = xr[64 * j]; s += (v[j].x + v[j].y) + (v[j].z + v[j].w); }
; DI void ln_phase(unsigned char* lds, int l, int which) {
;     ...
;         for (int m = MP + bid * 64 + wid; m < MP + bid * 64 + 64; m += 16) ln_row2(Y + (size_t)m * DM, Y + (size_t)(m + 8) * DM, XB + (size_t)m * DM, XB + (size_t)(m + 8) * DM, g, b, lane);
.Lmy_lns0_b1:
	s_cmp_ge_i32 s54, s52
	s_cbranch_scc1 .Lmy_lns0_n1
	global_load_dwordx4 v[36:39], v2, s[6:7]
	global_load_dwordx4 v[40:43], v2, s[6:7] offset:1024
	global_load_dwordx4 v[44:47], v2, s[6:7] offset:2048
	global_load_dwordx4 v[48:51], v2, s[6:7] offset:3072
	s_add_u32 s6, s6, s34
	s_addc_u32 s7, s7, 0
	s_add_i32 s54, s54, s5

; DI void ln_row(float* yrow, bf16_t* xb, const float* g, const float* b, int lane, float* yout = nullptr) {
;     ...
;     f32x4 v[4]; float s = 0.f;
; #pragma unroll
;     for (int j = 0; j < 4; ++j) { v[j] = xr[64 * j]; s += (v[j].x + v[j].y) + (v[j].z + v[j].w); }
; DI void ln_phase(unsigned char* lds, int l, int which) {
;     ...
;         for (int m = MP + bid * 64 + wid; m < MP + bid * 64 + 64; m += 16) ln_row2(Y + (size_t)m * DM, Y + (size_t)(m + 8) * DM, XB + (size_t)m * DM, XB + (size_t)(m + 8) * DM, g, b, lane);
.Lmy_lns0_b2:
	s_cmp_ge_i32 s54, s52
	s_cbranch_scc1 .Lmy_lns0_n2
	global_load_dwordx4 v[52:55], v2, s[6:7]
	global_load_dwordx4 v[56:59], v2, s[6:7] offset:1024
	global_load_dwordx4 v[60:63], v2, s[6:7] offset:2048
	global_load_dwordx4 v[64:67], v2, s[6:7] offset:3072
	s_add_u32 s6, s6, s34
	s_addc_u32 s7, s7, 0
	s_add_i32 s54, s54, s5

; DI void ln_row2(float* y0, float* y1, bf16_t* xb0, bf16_t* xb1, const float* g, const float* b, int lane) {
;     f32x4* xr0 = (f32x4*)y0 + lane; f32x4* xr1 = (f32x4*)y1 + lane;
;     f32x4 v0[4], v1[4]; float s0 = 0.f, s1 = 0.f;
; #pragma unroll
;     for (int j = 0; j < 4; ++j) { v0[j] = xr0[64 * j]; v1[j] = xr1[64 * j]; }
; DI void ln_phase(unsigned char* lds, int l, int which) {
;     ...
;         const int gw = (bid - 8) * 8 + wid, NGW = ((int)gridDim.x - 8) * 8;
;         if (REPS(3) > 1) for (int m = gw; m < MP; m += NGW) ln_row(Y + (size_t)m * DM, (bf16_t*)(ws + WS_OG) + (size_t)m * DM, g, b, lane, (float*)(ws + WS_BIG) + (size_t)m * DM);
;         int m = gw;
;         for (; m + NGW < MP; m += 2 * NGW) ln_row2(Y + (size_t)m * DM, Y + (size_t)(m + NGW) * DM, XB + (size_t)m * DM, XB + (size_t)(m + NGW) * DM, g, b, lane);
.Lmy_pfp1_j:
	s_add_u32 s48, s48, s100
	s_addc_u32 s49, s49, 0
	s_add_i32 s56, s57, 0
	v_lshrrev_b32_e32 v108, 3, v1
	v_mul_u32_u24_e32 v108, 2048, v108
	v_and_b32_e32 v109, 7, v1
	v_lshl_add_u32 v108, v109, 4, v108
	s_lshl_b32 s34, s5, 12
	s_lshl_b32 s35, s5, 11
	s_lshl_b32 s6, s4, 12
	s_add_u32 s8, s44, s6
	s_addc_u32 s9, s45, 0
	s_lshl_b32 s6, s4, 11
	s_add_u32 s10, s42, s6
	s_addc_u32 s11, s43, 0
	s_mov_b32 s6, s8
	s_mov_b32 s7, s9
	s_mov_b32 s54, s4
	global_load_dwordx4 v[36:39], v2, s[6:7]
	global_load_dwordx4 v[40:43], v2, s[6:7] offset:1024
	global_load_dwordx4 v[44:47], v2, s[6:7] offset:2048
	global_load_dwordx4 v[48:51], v2, s[6:7] offset:3072
	s_add_u32 s6, s6, s34
	s_addc_u32 s7, s7, 0
	s_add_i32 s54, s54, s5
	global_load_dwordx4 v[52:55], v2, s[6:7]
	global_load_dwordx4 v[56:59], v2, s[6:7] offset:1024
	global_load_dwordx4 v[60:63], v2, s[6:7] offset:2048
	global_load_dwordx4 v[64:67], v2, s[6:7] offset:3072
	s_add_u32 s6, s6, s34
	s_addc_u32 s7, s7, 0
	s_add_i32 s54, s54, s5
	s_waitcnt vmcnt(4)

; DI void ln_row2(float* y0, float* y1, bf16_t* xb0, bf16_t* xb1, const float* g, const float* b, int lane) {
;     f32x4* xr0 = (f32x4*)y0 + lane; f32x4* xr1 = (f32x4*)y1 + lane;
;     f32x4 v0[4], v1[4]; float s0 = 0.f, s1 = 0.f;
; #pragma unroll
;     for (int j = 0; j < 4; ++j) { v0[j] = xr0[64 * j]; v1[j] = xr1[64 * j]; }
; DI void ln_phase(unsigned char* lds, int l, int which) {
;     ...
;         __syncthreads();
;         for (int m = MP + bid * 64 + wid; m < MP + bid * 64 + 64; m += 16) ln_row2(Y + (size_t)m * DM, Y + (size_t)(m + 8) * DM, XB + (size_t)m * DM, XB + (size_t)(m + 8) * DM, g, b, lane);
.LBB0_2178:
	s_or_b64 exec, exec, s[40:41]
	s_lshl_b32 s4, s38, 6
	v_add_u32_e32 v2, s4, v162
	v_add_u32_e32 v34, 0x8000, v2
	s_add_i32 s4, s4, 0x8040
	v_cmp_gt_i32_e32 vcc, s4, v34
	s_barrier
	s_and_saveexec_b64 s[42:43], vcc
	s_mov_b32 s5, 0xf800000
	s_mov_b32 s8, 0x3a00000
	s_mov_b64 s[10:11], 0x8000
	s_mov_b64 s[50:51], 0x10000
	s_cbranch_execz .LBB0_2181
	s_mov_b64 s[42:43], exec
	s_add_u32 s50, s46, 0x3a00000
	s_addc_u32 s51, s47, 0
	v_readfirstlane_b32 s4, v162
	s_lshl_b32 s6, s38, 6
	s_add_i32 s4, s4, s6
	s_add_i32 s4, s4, 0x8000
	s_add_i32 s52, s6, 0x8040
	s_mov_b32 s5, 8
	v_lshlrev_b32_e32 v2, 4, v1
	v_lshlrev_b32_e32 v3, 3, v1
	global_load_dwordx4 v[4:7], v2, s[56:57]
	global_load_dwordx4 v[8:11], v2, s[56:57] offset:1024
	global_load_dwordx4 v[12:15], v2, s[56:57] offset:2048
	global_load_dwordx4 v[16:19], v2, s[56:57] offset:3072
	global_load_dwordx4 v[20:23], v2, s[48:49]
	global_load_dwordx4 v[24:27], v2, s[48:49] offset:1024
	global_load_dwordx4 v[28:31], v2, s[48:49] offset:2048
	global_load_dwordx4 v[32:35], v2, s[48:49] offset:3072
	s_lshl_b32 s34, s5, 12
	s_lshl_b32 s35, s5, 11
	s_lshl_b32 s6, s4, 12
	s_add_u32 s8, s44, s6
	s_addc_u32 s9, s45, 0
	s_lshl_b32 s6, s4, 11
	s_add_u32 s10, s50, s6
	s_addc_u32 s11, s51, 0
	s_mov_b32 s6, s8
	s_mov_b32 s7, s9
	s_mov_b32 s54, s4
	global_load_dwordx4 v[36:39], v2, s[6:7]
	global_load_dwordx4 v[40:43], v2, s[6:7] offset:1024
	global_load_dwordx4 v[44:47], v2, s[6:7] offset:2048
	global_load_dwordx4 v[48:51], v2, s[6:7] offset:3072
	s_add_u32 s6, s6, s34
	s_addc_u32 s7, s7, 0
	s_add_i32 s54, s54, s5
	global_load_dwordx4 v[52:55], v2, s[6:7]
	global_load_dwordx4 v[56:59], v2, s[6:7] offset:1024
	global_load_dwordx4 v[60:63], v2, s[6:7] offset:2048
	global_load_dwordx4 v[64:67], v2, s[6:7] offset:3072
	s_add_u32 s6, s6, s34
	s_addc_u32 s7, s7, 0
	s_add_i32 s54, s54, s5
	s_waitcnt vmcnt(4)

; DI void ln_row2(float* y0, float* y1, bf16_t* xb0, bf16_t* xb1, const float* g, const float* b, int lane) {
;     f32x4* xr0 = (f32x4*)y0 + lane; f32x4* xr1 = (f32x4*)y1 + lane;
;     f32x4 v0[4], v1[4]; float s0 = 0.f, s1 = 0.f;
; #pragma unroll
;     for (int j = 0; j < 4; ++j) { v0[j] = xr0[64 * j]; v1[j] = xr1[64 * j]; }
; DI void ln_phase(unsigned char* lds, int l, int which) {
;     ...
;         __syncthreads();
;         for (int m = MP + bid * 64 + wid; m < MP + bid * 64 + 64; m += 16) ln_row2(Y + (size_t)m * DM, Y + (size_t)(m + 8) * DM, XB + (size_t)m * DM, XB + (size_t)(m + 8) * DM, g, b, lane);
.LBB0_2449:
	s_or_b64 exec, exec, s[40:41]
	s_lshl_b32 s4, s70, 6
	v_add_u32_e32 v2, s4, v162
	v_add_u32_e32 v34, 0x8000, v2
	s_add_i32 s4, s4, 0x8040
	v_cmp_gt_i32_e32 vcc, s4, v34
	s_barrier
	s_and_saveexec_b64 s[42:43], vcc
	s_mov_b32 s5, 0xf800000
	s_mov_b32 s8, 0x3a00000
	s_mov_b64 s[10:11], 0x8000
	s_mov_b64 s[50:51], 0x10000
	s_cbranch_execz .LBB0_2452
	s_mov_b64 s[42:43], exec
	s_add_u32 s50, s46, 0x3a00000
	s_addc_u32 s51, s47, 0
	v_readfirstlane_b32 s4, v162
	s_lshl_b32 s6, s70, 6
	s_add_i32 s4, s4, s6
	s_add_i32 s4, s4, 0x8000
	s_add_i32 s52, s6, 0x8040
	s_mov_b32 s5, 8
	v_lshlrev_b32_e32 v2, 4, v1
	v_lshlrev_b32_e32 v3, 3, v1
	global_load_dwordx4 v[4:7], v2, s[56:57]
	global_load_dwordx4 v[8:11], v2, s[56:57] offset:1024
	global_load_dwordx4 v[12:15], v2, s[56:57] offset:2048
	global_load_dwordx4 v[16:19], v2, s[56:57] offset:3072
	global_load_dwordx4 v[20:23], v2, s[48:49]
	global_load_dwordx4 v[24:27], v2, s[48:49] offset:1024
	global_load_dwordx4 v[28:31], v2, s[48:49] offset:2048
	global_load_dwordx4 v[32:35], v2, s[48:49] offset:3072
	s_lshl_b32 s34, s5, 12
	s_lshl_b32 s35, s5, 11
	s_lshl_b32 s6, s4, 12
	s_add_u32 s8, s44, s6
	s_addc_u32 s9, s45, 0
	s_lshl_b32 s6, s4, 11
	s_add_u32 s10, s50, s6
	s_addc_u32 s11, s51, 0
	s_mov_b32 s6, s8
	s_mov_b32 s7, s9
	s_mov_b32 s54, s4
	global_load_dwordx4 v[36:39], v2, s[6:7]
	global_load_dwordx4 v[40:43], v2, s[6:7] offset:1024
	global_load_dwordx4 v[44:47], v2, s[6:7] offset:2048
	global_load_dwordx4 v[48:51], v2, s[6:7] offset:3072
	s_add_u32 s6, s6, s34
	s_addc_u32 s7, s7, 0
	s_add_i32 s54, s54, s5
	global_load_dwordx4 v[52:55], v2, s[6:7]
	global_load_dwordx4 v[56:59], v2, s[6:7] offset:1024
	global_load_dwordx4 v[60:63], v2, s[6:7] offset:2048
	global_load_dwordx4 v[64:67], v2, s[6:7] offset:3072
	s_add_u32 s6, s6, s34
	s_addc_u32 s7, s7, 0
	s_add_i32 s54, s54, s5
	s_waitcnt vmcnt(4)
